# grid barrier: extra un-waited L2 write-back by local arriver number 7*nloc/8
# baseline (speedup 1.0000x reference)
.LBB0_41:
	s_or_b64 exec, exec, s[6:7]
	v_cvt_f32_u32_e32 v6, v4
	s_waitcnt vmcnt(0)
	v_readfirstlane_b32 s6, v5
	v_sub_u32_e32 v5, 0, v4
	v_rcp_iflag_f32_e32 v6, v6
	v_add_u32_e32 v7, s6, v2
	v_mul_f32_e32 v6, 0x4f7ffffe, v6
	v_cvt_u32_f32_e32 v6, v6
	v_mul_lo_u32 v2, v5, v6
	v_mul_hi_u32 v2, v6, v2
	v_add_u32_e32 v2, v6, v2
	v_mul_hi_u32 v2, v7, v2
	v_mul_lo_u32 v5, v2, v4
	v_sub_u32_e32 v5, v7, v5
	v_add_u32_e32 v6, 1, v2
	v_sub_u32_e32 v8, v5, v4
	v_cmp_ge_u32_e32 vcc, v5, v4
	s_nop 1
	v_cndmask_b32_e32 v2, v2, v6, vcc
	v_cndmask_b32_e32 v5, v5, v8, vcc
	v_add_u32_e32 v6, 1, v2
	v_cmp_ge_u32_e32 vcc, v5, v4
	v_add_u32_e32 v5, 1, v7
	s_nop 0
	v_cndmask_b32_e32 v2, v2, v6, vcc
	v_mul_lo_u32 v6, v4, v2
	v_add_u32_e32 v4, v6, v4
	v_cmp_ne_u32_e32 vcc, v5, v4
	s_and_saveexec_b64 s[6:7], vcc
	s_xor_b64 s[6:7], exec, s[6:7]
	s_cbranch_execz .LBB0_55
	v_sub_u32_e32 v8, v4, v6
	v_sub_u32_e32 v6, v7, v6
	v_lshrrev_b32_e32 v9, 3, v8
	v_sub_u32_e32 v8, v8, v9
	v_cmp_eq_u32_e32 vcc, v6, v8
	s_cbranch_vccz .Lbar_nomidwb
	buffer_wbl2 sc1
